# P0 and P10 RMSNorm loops: loop-invariant gain-vector loads hoisted out of the row loops
# speedup vs baseline: 1.0080x; 1.0080x over previous
; DI unsigned pk2(float lo, float hi) { const f32x2 v = {lo, hi}; const hwbf16x2 b = __builtin_convertvector(v, hwbf16x2); return __builtin_bit_cast(unsigned, b); }
; DI float frcp(float x) { return __builtin_amdgcn_rcpf(x); }
; DI float frsq(float x) { return __builtin_amdgcn_rsqf(x); }
; DI void norm_row_bf16(const float* xrow, const float* g, bf16_t* orow, int lane, float* xs_out = nullptr) {
;     const f32x4* xr = (const f32x4*)xrow + lane; f32x4 v[8]; float s = 0.f;
; #pragma unroll
;     for (int j = 0; j < 8; ++j) { v[j] = xr[64 * j]; s += (v[j].x * v[j].x + v[j].y * v[j].y) + (v[j].z * v[j].z + v[j].w * v[j].w); }
;     s = wave_sum(s);
;     const float rs = frsq(s * (1.0f / DM) + 1e-6f);
;     if (xs_out && lane == 0) *xs_out = frcp(rs);
;     const f32x4* gr = (const f32x4*)g + lane;
;     u32x2* o8 = (u32x2*)orow + lane;
; #pragma unroll
;     for (int j = 0; j < 8; ++j) { const f32x4 gg = gr[64 * j]; u32x2 o; o.x = pk2(v[j].x * rs * gg.x, v[j].y * rs * gg.y); o.y = pk2(v[j].z * rs * gg.z, v[j].w * rs * gg.w); o8[64 * j] = o; }
; DI void prologue(const Params& p, LAS unsigned char* lds, int tid, int lane, int wave) {
;     ...
;     for (int m = gw; m < T_; m += NGW) norm_row_bf16(p.in[0] + (size_t)m * DM, p.in[1], HN + (size_t)m * DM, lane, XS + m);
.LBB0_111:
	s_cmpk_gt_i32 s6, 0x7fff
	v_mbcnt_lo_u32_b32 v169, -1, 0
	v_cmp_eq_u32_e32 vcc, 0, v1
	s_cbranch_scc1 .LBB0_116
	v_mbcnt_hi_u32_b32 v4, -1, v169
	v_and_b32_e32 v3, 64, v4
	v_add_u32_e32 v5, 64, v3
	v_xor_b32_e32 v3, 1, v4
	v_cmp_lt_i32_e64 s[0:1], v3, v5
	v_xor_b32_e32 v6, 2, v4
	v_lshlrev_b32_e32 v38, 4, v1
	v_cndmask_b32_e64 v3, v4, v3, s[0:1]
	v_cmp_lt_i32_e64 s[0:1], v6, v5
	v_mov_b32_e32 v39, 0
	v_lshl_add_u64 v[40:41], s[38:39], 0, v[38:39]
	v_cndmask_b32_e64 v6, v4, v6, s[0:1]
	v_lshlrev_b32_e32 v52, 2, v6
	v_xor_b32_e32 v6, 4, v4
	v_cmp_lt_i32_e64 s[0:1], v6, v5
	s_ashr_i32 s7, s6, 31
	s_mov_b64 s[8:9], 0x1000
	v_cndmask_b32_e64 v6, v4, v6, s[0:1]
	v_lshlrev_b32_e32 v53, 2, v6
	v_xor_b32_e32 v6, 8, v4
	v_cmp_lt_i32_e64 s[0:1], v6, v5
	v_lshl_add_u64 v[42:43], v[40:41], 0, s[8:9]
	v_mov_b32_e32 v37, v39
	v_cndmask_b32_e64 v6, v4, v6, s[0:1]
	v_lshlrev_b32_e32 v54, 2, v6
	v_xor_b32_e32 v6, 16, v4
	v_cmp_lt_i32_e64 s[0:1], v6, v5
	v_lshlrev_b32_e32 v3, 2, v3
	v_mov_b32_e32 v57, 0x358637bd
	v_cndmask_b32_e64 v6, v4, v6, s[0:1]
	v_lshlrev_b32_e32 v55, 2, v6
	v_xor_b32_e32 v6, 32, v4
	v_cmp_lt_i32_e64 s[0:1], v6, v5
	s_nop 1
	v_cndmask_b32_e64 v4, v4, v6, s[0:1]
	s_mov_b64 s[0:1], 0x1400
	v_lshl_add_u64 v[44:45], v[40:41], 0, s[0:1]
	s_mov_b64 s[0:1], 0x1800
	v_lshl_add_u64 v[46:47], v[40:41], 0, s[0:1]
	s_mov_b64 s[0:1], 0x1c00
	v_lshl_add_u64 v[48:49], v[40:41], 0, s[0:1]
	s_lshl_b64 s[0:1], s[6:7], 2
	s_add_u32 s0, s62, s0
	s_addc_u32 s1, s63, s1
	s_add_u32 s0, s0, 0x31b82000
	s_addc_u32 s1, s1, 0
	s_ashr_i32 s89, s88, 31
	s_lshl_b64 s[2:3], s[88:89], 2
	s_lshl_b64 s[10:11], s[6:7], 13
	s_add_u32 s10, s36, s10
	s_addc_u32 s11, s37, s11
	v_lshlrev_b32_e32 v56, 2, v4
	v_lshl_add_u64 v[4:5], s[10:11], 0, v[38:39]
	v_lshl_add_u64 v[50:51], v[4:5], 0, s[8:9]
	s_lshl_b64 s[8:9], s[88:89], 13
	s_lshl_b64 s[10:11], s[6:7], 12
	s_add_u32 s10, s62, s10
	s_addc_u32 s11, s63, s11
	v_lshl_add_u64 v[4:5], s[10:11], 0, v[36:37]
	s_mov_b64 s[10:11], 0x800
	v_lshl_add_u64 v[36:37], v[4:5], 0, s[10:11]
	s_lshl_b64 s[10:11], s[88:89], 12
	s_mov_b32 s7, s6
	global_load_dwordx4 v[80:83], v[40:41], off
	global_load_dwordx4 v[84:87], v[40:41], off offset:1024
	global_load_dwordx4 v[88:91], v[40:41], off offset:2048
	global_load_dwordx4 v[92:95], v[40:41], off offset:3072
	global_load_dwordx4 v[96:99], v[42:43], off
	global_load_dwordx4 v[100:103], v[44:45], off
	global_load_dwordx4 v[104:107], v[46:47], off
	global_load_dwordx4 v[108:111], v[48:49], off
	s_waitcnt vmcnt(0)
	s_branch .LBB0_114
.LBB0_113:
	s_or_b64 exec, exec, s[14:15]
	v_pk_mul_f32 v[32:33], v[32:33], v[38:39] op_sel_hi:[1,0]
	v_pk_mul_f32 v[34:35], v[34:35], v[38:39] op_sel_hi:[1,0]
	v_pk_mul_f32 v[28:29], v[28:29], v[38:39] op_sel_hi:[1,0]
	v_pk_mul_f32 v[30:31], v[30:31], v[38:39] op_sel_hi:[1,0]
	v_pk_mul_f32 v[24:25], v[24:25], v[38:39] op_sel_hi:[1,0]
	v_pk_mul_f32 v[26:27], v[26:27], v[38:39] op_sel_hi:[1,0]
	v_pk_mul_f32 v[20:21], v[20:21], v[38:39] op_sel_hi:[1,0]
	v_pk_mul_f32 v[22:23], v[22:23], v[38:39] op_sel_hi:[1,0]
	v_pk_mul_f32 v[16:17], v[16:17], v[38:39] op_sel_hi:[1,0]
	v_pk_mul_f32 v[18:19], v[18:19], v[38:39] op_sel_hi:[1,0]
	v_pk_mul_f32 v[12:13], v[12:13], v[38:39] op_sel_hi:[1,0]
	v_pk_mul_f32 v[14:15], v[14:15], v[38:39] op_sel_hi:[1,0]
	v_pk_mul_f32 v[8:9], v[8:9], v[38:39] op_sel_hi:[1,0]
	v_pk_mul_f32 v[10:11], v[10:11], v[38:39] op_sel_hi:[1,0]
	v_pk_mul_f32 v[4:5], v[4:5], v[38:39] op_sel_hi:[1,0]
	v_pk_mul_f32 v[6:7], v[6:7], v[38:39] op_sel_hi:[1,0]
	s_add_i32 s7, s7, s88
	s_add_u32 s0, s0, s2
	s_addc_u32 s1, s1, s3
	v_lshl_add_u64 v[50:51], v[50:51], 0, s[8:9]
	s_cmpk_gt_i32 s7, 0x7fff
	v_pk_mul_f32 v[32:33], v[32:33], v[80:81]
	v_pk_mul_f32 v[34:35], v[34:35], v[82:83]
	v_cvt_pk_bf16_f32 v32, v32, v33
	v_cvt_pk_bf16_f32 v33, v34, v35
	global_store_dwordx2 v[36:37], v[32:33], off offset:-2048
	v_pk_mul_f32 v[28:29], v[28:29], v[84:85]
	v_pk_mul_f32 v[30:31], v[30:31], v[86:87]
	v_cvt_pk_bf16_f32 v28, v28, v29
	v_cvt_pk_bf16_f32 v29, v30, v31
	global_store_dwordx2 v[36:37], v[28:29], off offset:-1536
	v_pk_mul_f32 v[24:25], v[24:25], v[88:89]
	v_pk_mul_f32 v[26:27], v[26:27], v[90:91]
	v_cvt_pk_bf16_f32 v24, v24, v25
	v_cvt_pk_bf16_f32 v25, v26, v27
	global_store_dwordx2 v[36:37], v[24:25], off offset:-1024
	v_pk_mul_f32 v[20:21], v[20:21], v[92:93]
	v_pk_mul_f32 v[22:23], v[22:23], v[94:95]
	v_cvt_pk_bf16_f32 v20, v20, v21
	v_cvt_pk_bf16_f32 v21, v22, v23
	global_store_dwordx2 v[36:37], v[20:21], off offset:-512
	v_pk_mul_f32 v[16:17], v[16:17], v[96:97]
	v_pk_mul_f32 v[18:19], v[18:19], v[98:99]
	v_cvt_pk_bf16_f32 v16, v16, v17
	v_cvt_pk_bf16_f32 v17, v18, v19
	global_store_dwordx2 v[36:37], v[16:17], off
	v_pk_mul_f32 v[12:13], v[12:13], v[100:101]
	v_pk_mul_f32 v[14:15], v[14:15], v[102:103]
	v_cvt_pk_bf16_f32 v12, v12, v13
	v_cvt_pk_bf16_f32 v13, v14, v15
	global_store_dwordx2 v[36:37], v[12:13], off offset:512
	v_pk_mul_f32 v[8:9], v[8:9], v[104:105]
	v_pk_mul_f32 v[10:11], v[10:11], v[106:107]
	v_cvt_pk_bf16_f32 v8, v8, v9
	v_cvt_pk_bf16_f32 v9, v10, v11
	global_store_dwordx2 v[36:37], v[8:9], off offset:1024
	v_pk_mul_f32 v[4:5], v[4:5], v[108:109]
	v_pk_mul_f32 v[6:7], v[6:7], v[110:111]
	v_cvt_pk_bf16_f32 v4, v4, v5
	v_cvt_pk_bf16_f32 v5, v6, v7
	global_store_dwordx2 v[36:37], v[4:5], off offset:1536
	v_lshl_add_u64 v[36:37], v[36:37], 0, s[10:11]
	s_cbranch_scc1 .LBB0_116

; DI float frsq(float x) { return __builtin_amdgcn_rsqf(x); }
; DI void norm_row_bf16_to_f32(const bf16_t* xrow, const float* g, float* orow, int lane) {
;     u32x4 v[4]; float s = 0.f;
; #pragma unroll
;     for (int j = 0; j < 4; ++j) {
;         v[j] = *((const u32x4*)xrow + lane + 64 * j);
;         float f;
;         f = bflo(v[j].x); s += f * f; f = bfhi(v[j].x); s += f * f; f = bflo(v[j].y); s += f * f; f = bfhi(v[j].y); s += f * f;
;         f = bflo(v[j].z); s += f * f; f = bfhi(v[j].z); s += f * f; f = bflo(v[j].w); s += f * f; f = bfhi(v[j].w); s += f * f;
;     }
;     s = wave_sum(s);
;     const float rs = frsq(s * (1.0f / DM) + 1e-6f);
; #pragma unroll
;     for (int j = 0; j < 4; ++j) {
;         const f32x4 g0 = *((const f32x4*)g + 2 * (lane + 64 * j)), g1 = *((const f32x4*)g + 2 * (lane + 64 * j) + 1);
; __global__ void __launch_bounds__(NTHREADS, 2) fwd_megakernel(Params p) {
;     ...
;     {
;         PHASE_IDS;
;         const int gw = bid * 8 + wave, NGW = G * 8;
;         for (int m = gw; m < T_; m += NGW) norm_row_bf16_to_f32(HN + (size_t)m * DM, p.in[19], p.out + (size_t)m * DM, lane);
.LBB0_1160:
	s_or_b64 exec, exec, s[2:3]
	s_waitcnt lgkmcnt(0)
	s_barrier
	v_readlane_b32 s2, v234, 10
	v_readfirstlane_b32 s0, v167
	s_ashr_i32 s0, s0, 6
	s_add_i32 s4, s0, s2
	s_cmpk_gt_i32 s4, 0x7fff
	s_cbranch_scc1 .LBB0_1163
	v_mbcnt_hi_u32_b32 v0, -1, v169
	v_and_b32_e32 v1, 64, v0
	v_add_u32_e32 v1, 64, v1
	v_xor_b32_e32 v2, 1, v0
	v_cmp_lt_i32_e32 vcc, v2, v1
	s_ashr_i32 s1, s0, 31
	s_ashr_i32 s3, s2, 31
	v_cndmask_b32_e32 v2, v0, v2, vcc
	v_lshlrev_b32_e32 v10, 2, v2
	v_xor_b32_e32 v2, 2, v0
	v_cmp_lt_i32_e32 vcc, v2, v1
	s_add_u32 s2, s0, s2
	s_addc_u32 s3, s1, s3
	v_cndmask_b32_e32 v2, v0, v2, vcc
	v_lshlrev_b32_e32 v11, 2, v2
	v_xor_b32_e32 v2, 4, v0
	v_cmp_lt_i32_e32 vcc, v2, v1
	s_lshl_b64 s[0:1], s[2:3], 13
	v_and_b32_e32 v16, 63, v167
	v_cndmask_b32_e32 v2, v0, v2, vcc
	v_lshlrev_b32_e32 v12, 2, v2
	v_xor_b32_e32 v2, 8, v0
	v_cmp_lt_i32_e32 vcc, v2, v1
	s_add_u32 s0, s60, s0
	v_lshlrev_b32_e32 v8, 5, v16
	v_cndmask_b32_e32 v2, v0, v2, vcc
	v_lshlrev_b32_e32 v13, 2, v2
	v_xor_b32_e32 v2, 16, v0
	v_cmp_lt_i32_e32 vcc, v2, v1
	v_mov_b32_e32 v9, 0
	s_addc_u32 s1, s61, s1
	v_cndmask_b32_e32 v2, v0, v2, vcc
	v_lshlrev_b32_e32 v14, 2, v2
	v_xor_b32_e32 v2, 32, v0
	v_readlane_b32 s8, v234, 0
	v_lshl_add_u64 v[6:7], s[0:1], 0, v[8:9]
	s_mov_b64 s[0:1], 0x1000
	s_ashr_i32 s59, s58, 31
	v_cmp_lt_i32_e32 vcc, v2, v1
	v_readlane_b32 s14, v234, 6
	v_readlane_b32 s15, v234, 7
	v_lshl_add_u64 v[6:7], v[6:7], 0, s[0:1]
	s_lshl_b64 s[0:1], s[58:59], 13
	s_lshl_b64 s[2:3], s[2:3], 12
	v_cndmask_b32_e32 v0, v0, v2, vcc
	s_mov_b64 s[6:7], s[14:15]
	s_add_u32 s2, s62, s2
	v_lshlrev_b32_e32 v15, 2, v0
	v_lshl_add_u64 v[0:1], s[6:7], 0, v[8:9]
	v_or_b32_e32 v2, 0x1000, v8
	v_or_b32_e32 v4, 0x1800, v8
	v_lshlrev_b32_e32 v8, 4, v16
	s_addc_u32 s3, s63, s3
	v_mov_b32_e32 v3, v9
	v_mov_b32_e32 v5, v9
	v_lshl_add_u64 v[8:9], s[2:3], 0, v[8:9]
	s_mov_b64 s[2:3], 0xc00
	v_lshl_add_u64 v[2:3], s[6:7], 0, v[2:3]
	v_lshl_add_u64 v[4:5], s[6:7], 0, v[4:5]
	v_lshl_add_u64 v[8:9], v[8:9], 0, s[2:3]
	s_lshl_b64 s[2:3], s[58:59], 12
	v_mov_b32_e32 v16, 0x358637bd
	v_readlane_b32 s9, v234, 1
	v_readlane_b32 s10, v234, 2
	v_readlane_b32 s11, v234, 3
	v_readlane_b32 s12, v234, 4
	v_readlane_b32 s13, v234, 5
	global_load_dwordx4 v[96:99], v[0:1], off
	global_load_dwordx4 v[100:103], v[0:1], off offset:16
	global_load_dwordx4 v[104:107], v[0:1], off offset:2048
	global_load_dwordx4 v[108:111], v[0:1], off offset:2064
	global_load_dwordx4 v[112:115], v[2:3], off
	global_load_dwordx4 v[116:119], v[2:3], off offset:16
	global_load_dwordx4 v[120:123], v[4:5], off
	global_load_dwordx4 v[124:127], v[4:5], off offset:16
	s_waitcnt vmcnt(0)
; DI float frsq(float x) { return __builtin_amdgcn_rsqf(x); }
; DI void norm_row_bf16_to_f32(const bf16_t* xrow, const float* g, float* orow, int lane) {
;     u32x4 v[4]; float s = 0.f;
; #pragma unroll
;     for (int j = 0; j < 4; ++j) {
;         v[j] = *((const u32x4*)xrow + lane + 64 * j);
;         float f;
;         f = bflo(v[j].x); s += f * f; f = bfhi(v[j].x); s += f * f; f = bflo(v[j].y); s += f * f; f = bfhi(v[j].y); s += f * f;
;         f = bflo(v[j].z); s += f * f; f = bfhi(v[j].z); s += f * f; f = bflo(v[j].w); s += f * f; f = bfhi(v[j].w); s += f * f;
;     }
;     s = wave_sum(s);
;     const float rs = frsq(s * (1.0f / DM) + 1e-6f);
; #pragma unroll
;     for (int j = 0; j < 4; ++j) {
;         const f32x4 g0 = *((const f32x4*)g + 2 * (lane + 64 * j)), g1 = *((const f32x4*)g + 2 * (lane + 64 * j) + 1);
;         f32x4 o0, o1;
;         o0.x = bflo(v[j].x) * rs * g0.x; o0.y = bfhi(v[j].x) * rs * g0.y; o0.z = bflo(v[j].y) * rs * g0.z; o0.w = bfhi(v[j].y) * rs * g0.w;
;         o1.x = bflo(v[j].z) * rs * g1.x; o1.y = bfhi(v[j].z) * rs * g1.y; o1.z = bflo(v[j].w) * rs * g1.z; o1.w = bfhi(v[j].w) * rs * g1.w;
;         *((f32x4*)orow + 2 * (lane + 64 * j)) = o0; *((f32x4*)orow + 2 * (lane + 64 * j) + 1) = o1;
;     }
.LBB0_1162:
	global_load_dwordx4 v[18:21], v[8:9], off
	global_load_dwordx4 v[22:25], v[8:9], off offset:-3072
	global_load_dwordx4 v[26:29], v[8:9], off offset:-2048
	global_load_dwordx4 v[30:33], v[8:9], off offset:-1024
	s_add_i32 s4, s4, s58
	v_lshl_add_u64 v[8:9], v[8:9], 0, s[2:3]
	s_cmpk_gt_i32 s4, 0x7fff
	s_waitcnt vmcnt(3)
	v_and_b32_e32 v42, 0xffff0000, v21
	s_waitcnt vmcnt(2)
	v_lshlrev_b32_e32 v46, 16, v22
	v_and_b32_e32 v47, 0xffff0000, v22
	v_lshlrev_b32_e32 v22, 16, v23
	v_and_b32_e32 v23, 0xffff0000, v23
	v_pk_mul_f32 v[64:65], v[46:47], v[46:47]
	v_pk_mul_f32 v[66:67], v[22:23], v[22:23]
	v_add_f32_e32 v17, v65, v64
	v_lshlrev_b32_e32 v44, 16, v24
	v_and_b32_e32 v45, 0xffff0000, v24
	v_add_f32_e32 v17, v66, v17
	v_lshlrev_b32_e32 v43, 16, v21
	v_lshlrev_b32_e32 v56, 16, v20
	v_and_b32_e32 v57, 0xffff0000, v20
	v_pk_mul_f32 v[20:21], v[44:45], v[44:45]
	v_add_f32_e32 v17, v67, v17
	v_lshlrev_b32_e32 v24, 16, v25
	v_and_b32_e32 v25, 0xffff0000, v25
	v_add_f32_e32 v17, v20, v17
	v_pk_mul_f32 v[62:63], v[24:25], v[24:25]
	v_add_f32_e32 v17, v21, v17
	s_waitcnt vmcnt(1)
	v_lshlrev_b32_e32 v50, 16, v26
	v_and_b32_e32 v51, 0xffff0000, v26
	v_add_f32_e32 v17, v62, v17
	v_pk_mul_f32 v[72:73], v[50:51], v[50:51]
	v_add_f32_e32 v17, v63, v17
	v_lshlrev_b32_e32 v26, 16, v27
	v_and_b32_e32 v27, 0xffff0000, v27
	v_add_f32_e32 v17, v72, v17
	v_pk_mul_f32 v[74:75], v[26:27], v[26:27]
	v_add_f32_e32 v17, v73, v17
	v_lshlrev_b32_e32 v48, 16, v28
	v_and_b32_e32 v49, 0xffff0000, v28
	v_add_f32_e32 v17, v74, v17
	v_pk_mul_f32 v[68:69], v[48:49], v[48:49]
	v_add_f32_e32 v17, v75, v17
	v_lshlrev_b32_e32 v28, 16, v29
	v_and_b32_e32 v29, 0xffff0000, v29
	v_add_f32_e32 v17, v68, v17
	v_pk_mul_f32 v[70:71], v[28:29], v[28:29]
	v_add_f32_e32 v17, v69, v17
	s_waitcnt vmcnt(0)
	v_lshlrev_b32_e32 v54, 16, v30
	v_and_b32_e32 v55, 0xffff0000, v30
	v_add_f32_e32 v17, v70, v17
	v_pk_mul_f32 v[80:81], v[54:55], v[54:55]
	v_add_f32_e32 v17, v71, v17
	v_lshlrev_b32_e32 v30, 16, v31
	v_and_b32_e32 v31, 0xffff0000, v31
	v_add_f32_e32 v17, v80, v17
	v_pk_mul_f32 v[82:83], v[30:31], v[30:31]
	v_add_f32_e32 v17, v81, v17
	v_lshlrev_b32_e32 v52, 16, v32
	v_and_b32_e32 v53, 0xffff0000, v32
	v_add_f32_e32 v17, v82, v17
	v_pk_mul_f32 v[76:77], v[52:53], v[52:53]
	v_add_f32_e32 v17, v83, v17
	v_lshlrev_b32_e32 v32, 16, v33
	v_and_b32_e32 v33, 0xffff0000, v33
	v_add_f32_e32 v17, v76, v17
	v_pk_mul_f32 v[78:79], v[32:33], v[32:33]
	v_add_f32_e32 v17, v77, v17
	v_lshlrev_b32_e32 v58, 16, v18
	v_and_b32_e32 v59, 0xffff0000, v18
	v_add_f32_e32 v17, v78, v17
	v_pk_mul_f32 v[86:87], v[58:59], v[58:59]
	v_add_f32_e32 v17, v79, v17
	v_lshlrev_b32_e32 v60, 16, v19
	v_and_b32_e32 v61, 0xffff0000, v19
	v_add_f32_e32 v17, v86, v17
	v_pk_mul_f32 v[88:89], v[60:61], v[60:61]
	v_add_f32_e32 v17, v87, v17
	v_add_f32_e32 v17, v88, v17
	v_pk_mul_f32 v[84:85], v[56:57], v[56:57]
	v_add_f32_e32 v17, v89, v17
	v_add_f32_e32 v17, v84, v17
	v_pk_mul_f32 v[18:19], v[42:43], v[42:43]
	v_add_f32_e32 v17, v85, v17
	v_add_f32_e32 v17, v19, v17
	v_add_f32_e32 v17, v18, v17
	ds_bpermute_b32 v18, v10, v17
	s_waitcnt lgkmcnt(0)
	v_add_f32_e32 v17, v17, v18
	ds_bpermute_b32 v18, v11, v17
	s_waitcnt lgkmcnt(0)
	v_add_f32_e32 v17, v17, v18
	ds_bpermute_b32 v18, v12, v17
	s_waitcnt lgkmcnt(0)
	v_add_f32_e32 v17, v17, v18
	ds_bpermute_b32 v18, v13, v17
	s_waitcnt lgkmcnt(0)
	v_add_f32_e32 v17, v17, v18
	ds_bpermute_b32 v18, v14, v17
	s_waitcnt lgkmcnt(0)
	v_add_f32_e32 v17, v17, v18
	ds_bpermute_b32 v18, v15, v17
	s_waitcnt lgkmcnt(0)
	v_add_f32_e32 v17, v17, v18
	v_fmamk_f32 v17, v17, 0x3a000000, v16
	v_rsq_f32_e32 v62, v17
	s_nop 0
	v_pk_mul_f32 v[18:19], v[62:63], v[46:47] op_sel_hi:[0,1]
	v_pk_mul_f32 v[20:21], v[62:63], v[22:23] op_sel_hi:[0,1]
	v_pk_mul_f32 v[22:23], v[62:63], v[44:45] op_sel_hi:[0,1]
	v_pk_mul_f32 v[24:25], v[62:63], v[24:25] op_sel_hi:[0,1]
	v_pk_mul_f32 v[20:21], v[98:99], v[20:21]
	v_pk_mul_f32 v[18:19], v[96:97], v[18:19]
	v_pk_mul_f32 v[24:25], v[102:103], v[24:25]
	v_pk_mul_f32 v[22:23], v[100:101], v[22:23]
	global_store_dwordx4 v[6:7], v[18:21], off offset:-4096
	global_store_dwordx4 v[6:7], v[22:25], off offset:-4080
	v_pk_mul_f32 v[26:27], v[62:63], v[26:27] op_sel_hi:[0,1]
	v_pk_mul_f32 v[34:35], v[62:63], v[50:51] op_sel_hi:[0,1]
	v_pk_mul_f32 v[28:29], v[62:63], v[28:29] op_sel_hi:[0,1]
	v_pk_mul_f32 v[36:37], v[62:63], v[48:49] op_sel_hi:[0,1]
	v_pk_mul_f32 v[18:19], v[104:105], v[34:35]
	v_pk_mul_f32 v[20:21], v[106:107], v[26:27]
	v_pk_mul_f32 v[22:23], v[108:109], v[36:37]
	v_pk_mul_f32 v[24:25], v[110:111], v[28:29]
	global_store_dwordx4 v[6:7], v[18:21], off offset:-2048
	global_store_dwordx4 v[6:7], v[22:25], off offset:-2032
	v_pk_mul_f32 v[26:27], v[62:63], v[30:31] op_sel_hi:[0,1]
	v_pk_mul_f32 v[28:29], v[62:63], v[54:55] op_sel_hi:[0,1]
	v_pk_mul_f32 v[30:31], v[62:63], v[32:33] op_sel_hi:[0,1]
	v_pk_mul_f32 v[32:33], v[62:63], v[52:53] op_sel_hi:[0,1]
	v_pk_mul_f32 v[18:19], v[112:113], v[28:29]
	v_pk_mul_f32 v[20:21], v[114:115], v[26:27]
	v_pk_mul_f32 v[22:23], v[116:117], v[32:33]
	v_pk_mul_f32 v[24:25], v[118:119], v[30:31]
	global_store_dwordx4 v[6:7], v[18:21], off
	global_store_dwordx4 v[6:7], v[22:25], off offset:16
	v_pk_mul_f32 v[26:27], v[62:63], v[60:61] op_sel_hi:[0,1]
	v_pk_mul_f32 v[28:29], v[62:63], v[58:59] op_sel_hi:[0,1]
	v_pk_mul_f32 v[30:31], v[62:63], v[56:57] op_sel_hi:[0,1]
	v_pk_mul_f32 v[32:33], v[62:63], v[42:43] op_sel_hi:[0,1]
	v_pk_mul_f32 v[18:19], v[120:121], v[28:29]
	v_pk_mul_f32 v[20:21], v[122:123], v[26:27]
	v_pk_mul_f32 v[22:23], v[124:125], v[30:31]
	v_pk_mul_f32 v[24:25], v[126:127], v[32:33] op_sel:[0,1] op_sel_hi:[1,0]
	global_store_dwordx4 v[6:7], v[18:21], off offset:2048
	global_store_dwordx4 v[6:7], v[22:25], off offset:2064
	v_lshl_add_u64 v[6:7], v[6:7], 0, s[0:1]
	s_cbranch_scc0 .LBB0_1162
